# decode waves of the non-scan workgroups run at s_setprio 3 (memory stream with little VALU beside the attention waves)
# baseline (speedup 1.0000x reference)
; #define LAS __attribute__((address_space(3)))
; __device__ __forceinline__ unsigned xb_ld(unsigned* p)              { return __hip_atomic_load(p, __ATOMIC_RELAXED, __HIP_MEMORY_SCOPE_AGENT); }
; #define XB_SPIN(cond, bar) do { unsigned _sp = 0; while (cond) { __builtin_amdgcn_s_sleep(1); \
;     if ((++_sp & 255u) == 0u) { if (xb_ld(&(bar)[XB_TMO])) break; if (_sp > XB_SPIN_CAP) { atomicAdd(&(bar)[XB_TMO], 1u); break; } } } } while (0)
; __device__ __forceinline__ void sb_decode_wave_loop(const Params& P, float* lds) {
;     unsigned* qd = (unsigned*)(P.ws + WS_BAR) + QW_DEC;
;     const int lane = threadIdx.x & 63;
;     volatile LAS unsigned* scw = (volatile LAS unsigned*)((LAS unsigned char*)lds + SC_CTL_OFF_FWD);
;     unsigned nxt = 0u;
;     if (lane == 0) nxt = atomicAdd(qd, 2u);
;     for (;;) {
;         const int t = __builtin_amdgcn_readfirstlane((int)nxt);
;         if (t >= DEC_NTASK) break;
;         if (lane == 0) nxt = atomicAdd(qd, 2u);
; __device__ __forceinline__ void p3_scan_and_sb(const Params& P, float* lds) {
;     const int tid = threadIdx.x, lane = tid & 63, wave = tid >> 6;
;     unsigned* ctl = (unsigned*)(P.ws + WS_BAR);
;     __syncthreads();
;     if (blockIdx.x < 96) {
;         const int bh = blockIdx.x >> 2, quarter = blockIdx.x & 3, b = bh / RH, h = bh % RH;
;         volatile LAS unsigned* scw = (volatile LAS unsigned*)((LAS unsigned char*)lds + SC_CTL_OFF);
;         if (tid < 5) scw[tid] = 0u;
;         if (tid == 0) { XB_SPIN(xb_ld(ctl + QW_PREP_W) < (unsigned)NPREP, ctl); __builtin_amdgcn_fence(__ATOMIC_ACQUIRE, "agent"); asm volatile("s_waitcnt vmcnt(0)" ::: "memory"); }
;         __syncthreads();
;         scan_prompt_wave(P, (unsigned char*)lds, b, h, quarter);
;         if (wave >= 5 + SC_FREE_WAVES) {
;             constexpr unsigned NCHU = SEQ / SCH;
;             while (scw[1] < NCHU || scw[2] < NCHU || scw[3] < NCHU || scw[4] < NCHU) __builtin_amdgcn_s_sleep(32);
;         }
;     } else {
;         const int grp = wave >> 2, gw = wave & 3;
;         volatile LAS unsigned* gctl = (volatile LAS unsigned*)((LAS unsigned char*)lds + LDS_CTL + 32);
;         if (tid < 8) gctl[tid] = 0u;
;         __syncthreads();
;         sba::Grp4 G; G.ctr = gctl + grp; G.gen = 0u;
;         if (grp == 1) sb_decode_wave_loop(P, lds);
.LBB0_939:
	s_cmp_lt_i32 s60, 4
	s_cselect_b64 s[0:1], -1, 0
	s_cmp_gt_i32 s61, 3
	s_cselect_b64 s[2:3], -1, 0
	s_and_b64 s[34:35], s[0:1], s[2:3]
	s_andn2_b64 vcc, exec, s[34:35]
	s_cbranch_vccnz .LBB0_1576
	v_writelane_b32 v252, s34, 54
	s_cmpk_lt_u32 s56, 0x60
	v_and_b32_e32 v1, 63, v0
	v_writelane_b32 v252, s35, 55
	v_writelane_b32 v252, s80, 56
	s_cselect_b64 s[52:53], -1, 0
	s_cmpk_gt_u32 s56, 0x5f
	v_writelane_b32 v252, s81, 57
	v_writelane_b32 v252, s56, 53
	v_writelane_b32 v252, s60, 51
	s_mov_b64 s[0:1], -1
	s_waitcnt vmcnt(0)
	v_writelane_b32 v252, s61, 52
	s_barrier
	v_writelane_b32 v252, s57, 50
	s_cbranch_scc0 .LBB0_1203
	v_writelane_b32 v252, s52, 58
	v_cmp_gt_u32_e32 vcc, 8, v0
	s_nop 0
	v_writelane_b32 v252, s53, 59
	s_and_saveexec_b64 s[0:1], vcc
	v_lshl_add_u32 v2, v0, 2, 0
	v_add_u32_e32 v2, 0x26020, v2
	v_mov_b32_e32 v3, 0
	ds_write_b32 v2, v3
	s_or_b64 exec, exec, s[0:1]
	v_lshrrev_b32_e32 v94, 8, v0
	s_waitcnt lgkmcnt(0)
	s_barrier
	v_cmp_eq_u32_e32 vcc, 1, v94
	s_mov_b64 s[0:1], exec
	v_writelane_b32 v252, s0, 60
	s_nop 1
	v_writelane_b32 v252, s1, 61
	s_and_b64 s[0:1], s[0:1], vcc
	s_mov_b64 exec, s[0:1]
	s_cbranch_execz .LBB0_1092
	s_setprio 3
	s_add_u32 s0, s78, 0x3900
	s_addc_u32 s1, s79, 0
	v_writelane_b32 v252, s0, 62
	v_mov_b32_e32 v95, 0
	v_cmp_eq_u32_e64 s[4:5], 0, v1
	v_writelane_b32 v252, s1, 63
	s_and_saveexec_b64 s[0:1], s[4:5]
	v_readlane_b32 s22, v252, 48
	v_readlane_b32 s23, v252, 49
	s_cbranch_execz .LBB0_948
	s_mov_b64 s[6:7], exec
	v_mbcnt_lo_u32_b32 v2, s6, 0
	v_mbcnt_hi_u32_b32 v2, s7, v2
	v_cmp_eq_u32_e32 vcc, 0, v2
	s_and_saveexec_b64 s[2:3], vcc
	s_cbranch_execz .LBB0_947
	s_bcnt1_i32_b64 s6, s[6:7]
	s_lshl_b32 s6, s6, 1
	v_mov_b32_e32 v4, s6
	v_readlane_b32 s6, v252, 62
	v_mov_b32_e32 v3, 0
	v_readlane_b32 s7, v252, 63
	s_nop 4
	global_atomic_add v3, v3, v4, s[6:7] sc0

; #define LAS __attribute__((address_space(3)))
; __device__ __forceinline__ void p3_scan_and_sb(const Params& P, float* lds) {
;     ...
;         if (grp == 1) sb_decode_wave_loop(P, lds);
;         {
;             volatile LAS unsigned* qw = gctl + 4 + grp;
;             unsigned* qhead = (unsigned*)(P.ws + WS_BAR) + QW_SB;
;             const bool popper = (gw == 0 && lane == 0);
;             unsigned nxt = 0u;
;             if (popper) nxt = atomicAdd(qhead, 1u);
.LBB0_1092:
	s_setprio 0
	v_readlane_b32 s0, v252, 60
	v_readlane_b32 s1, v252, 61
	s_or_b64 exec, exec, s[0:1]
	v_bfe_u32 v2, v0, 6, 2
	s_add_u32 s0, s78, 0x3800
	s_addc_u32 s1, s79, 0
	v_or_b32_e32 v3, v2, v1
	v_writelane_b32 v252, s0, 60
	v_mov_b32_e32 v153, 0
	v_cmp_eq_u32_e32 vcc, 0, v3
	v_writelane_b32 v252, s1, 61
	s_and_saveexec_b64 s[0:1], vcc
	s_cbranch_execz .LBB0_1096
	s_mov_b64 s[6:7], exec
	v_mbcnt_lo_u32_b32 v3, s6, 0
	v_mbcnt_hi_u32_b32 v3, s7, v3
	v_cmp_eq_u32_e64 s[4:5], 0, v3
	s_and_saveexec_b64 s[2:3], s[4:5]
	s_cbranch_execz .LBB0_1095
	s_bcnt1_i32_b64 s4, s[6:7]
	v_mov_b32_e32 v5, s4
	v_readlane_b32 s4, v252, 60
	v_mov_b32_e32 v4, 0
	v_readlane_b32 s5, v252, 61
	s_nop 4
	global_atomic_add v4, v4, v5, s[4:5] sc0
